# in0 GEMM epilogue: lane-split row-scale loads reduced once, section destinations chosen by scalar branches (no per-row dependent load chain)
# speedup vs baseline: 1.0326x; 1.0036x over previous
;     __device__ __forceinline__ void operator()(AccRef acc, const pg8::Unit& u, int wr, int wc, int fr, int fq) const {
;         const int sec = u.pn >> 1;
;         const int row0 = u.pm * 256 + wr * 64 + fr, cs0 = (u.pn & 1) * 256 + wc * 32 + 8 * fq;
;         const bool sample = (u.pm == 128);
;         bf16_t* tok = (bf16_t*)(ws + WS_QA + (size_t)sec * QKV_SZ);
;         const float qs = (sec == 0 || sec == 3) ? QS_AB : 1.0f;
; #pragma unroll
;         for (int ai = 0; ai < 2; ++ai)
; #pragma unroll
;             for (int m = 0; m < 4; ++m) {
;                 const int row = row0 + ai * 128 + m * 16;
;                 const float rs = rs_from(ssp + (size_t)row * 16, 4, 1.0f / 1024.0f);
;                 const float sc = rs * qs;
; #pragma unroll
;                 for (int bj = 0; bj < 2; ++bj) {
;                     const int cs = cs0 + bj * 128;
;                     const f32x4 a = acc[ai][bj][m][0] * sc, b = acc[ai][bj][m][1] * sc;
;                     const u32x4 w = pack8(a, b);
;                     *(u32x4*)(tok + (size_t)row * 512 + cs) = w;
;                     if (sec == 0 || sec == 3) continue;
;                     float* fo = nullptr;
;                     if (!sample) {
;                         const int b_ = row >> 11, t = row & 2047;
;                         if (sec == 1 || sec == 2) { if ((u.pm & 7) >= 6) fo = out + (sec == 1 ? O_PAK : O_PAV) + ((size_t)b_ * 512 + (t - 1536)) * 512 + cs; }
;                         else fo = out + (sec == 4 ? O_PBK : O_PBV) + (size_t)row * 512 + cs;
;                     } else {
;                         const int sr = row - TP, b_ = sr >> 4, t = sr & 15;
;                         const size_t so = (sec == 1) ? O_SAK : (sec == 2) ? O_SAV : (sec == 4) ? O_SBK : O_SBV;
;                         fo = out + so + (size_t)sr * 512 + cs;
;                         bf16_t* cat = (sec == 1) ? (bf16_t*)(ws + WS_KAS) + ((size_t)b_ * KA_ROWS + 512 + t) * 512
;                                     : (sec == 2) ? (bf16_t*)(ws + WS_VAS) + ((size_t)b_ * KA_ROWS + 512 + t) * 512
;                                     : (sec == 4) ? (bf16_t*)(ws + WS_KBS) + ((size_t)b_ * KB_ROWS + 1024 + t) * 512
;                                                  : (bf16_t*)(ws + WS_VBS) + ((size_t)b_ * KB_ROWS + 1024 + t) * 512;
;                         *(u32x4*)(cat + cs) = w;
;                     }
.LBB0_600:
.Lin0_beg:
	s_lshl_b32 s4, s26, 8
	s_add_i32 s4, s4, s76
	v_or_b32_e32 v246, s4, v174
	v_and_b32_e32 v247, 24, v176
	v_lshlrev_b32_e32 v247, 1, v247
	v_lshl_add_u32 v247, v246, 6, v247
	v_add_u32_e32 v249, 0x2000, v247
	global_load_dwordx4 v[128:131], v247, s[46:47]
	global_load_dwordx4 v[156:159], v247, s[46:47] offset:1024
	global_load_dwordx4 v[160:163], v247, s[46:47] offset:2048
	global_load_dwordx4 v[164:167], v247, s[46:47] offset:3072
	global_load_dwordx4 v[168:171], v249, s[46:47]
	global_load_dwordx4 v[184:187], v249, s[46:47] offset:1024
	global_load_dwordx4 v[188:191], v249, s[46:47] offset:2048
	global_load_dwordx4 v[192:195], v249, s[46:47] offset:3072
	v_mbcnt_lo_u32_b32 v196, -1, 0
	v_mbcnt_hi_u32_b32 v196, -1, v196
	v_xor_b32_e32 v197, 16, v196
	v_xor_b32_e32 v198, 32, v196
	v_lshlrev_b32_e32 v197, 2, v197
	v_lshlrev_b32_e32 v198, 2, v198
	s_lshr_b32 s27, s8, 1
	s_and_b32 s28, s8, 1
	s_lshl_b32 s28, s28, 8
	v_add_u32_e32 v248, s28, v176
	v_lshlrev_b32_e32 v250, 1, v248
	v_lshl_add_u32 v250, v246, 10, v250
	v_lshlrev_b32_e32 v251, 2, v248
	v_lshl_add_u32 v251, v246, 11, v251
	s_mul_i32 s28, s27, 0x2040000
	s_add_u32 s28, s28, 0xd604000
	s_add_u32 s50, s88, s28
	s_addc_u32 s51, s89, 0
	s_cmp_eq_u32 s27, 0
	s_cselect_b32 s29, 1, 0
	s_cmp_eq_u32 s27, 3
	s_cselect_b32 s29, 1, s29
	s_mov_b32 s38, 0
	s_cmp_lt_u32 s27, 4
	s_cbranch_scc1 .Lin0_a
	s_mov_b32 s38, 1
	s_mov_b32 s39, 0xe100000
	s_cmp_eq_u32 s27, 4
	s_cselect_b32 s39, 0xa100000, s39
	s_add_u32 s58, s54, s39
	s_addc_u32 s59, s55, 0
	s_branch .Lin0_b
.Lin0_a:
	s_cmp_eq_u32 s29, 1
	s_cbranch_scc1 .Lin0_b
	s_and_b32 s39, s26, 7
	s_cmp_ge_u32 s39, 6
	s_cbranch_scc0 .Lin0_b
	s_mov_b32 s38, 1
	s_mov_b32 s39, 0x9100000
	s_cmp_eq_u32 s27, 1
	s_cselect_b32 s39, 0x8100000, s39
	s_lshr_b32 s40, s26, 3
	s_add_u32 s40, s40, 1
	s_mul_i32 s40, s40, 0x300000
	s_sub_u32 s39, s39, s40
	s_ashr_i32 s41, s39, 31
	s_add_u32 s58, s54, s39
	s_addc_u32 s59, s55, s41
.Lin0_b:
	v_mov_b32_e32 v199, 1.0
	s_cmp_eq_u32 s29, 1
	s_cbranch_scc0 .Lin0_c
	v_mov_b32_e32 v199, v182
.Lin0_c:
	s_waitcnt vmcnt(0)
	v_add_f32_e32 v128, v128, v129
	v_add_f32_e32 v130, v130, v131
	v_add_f32_e32 v156, v156, v157
	v_add_f32_e32 v158, v158, v159
	v_add_f32_e32 v160, v160, v161
	v_add_f32_e32 v162, v162, v163
	v_add_f32_e32 v164, v164, v165
	v_add_f32_e32 v166, v166, v167
	v_add_f32_e32 v168, v168, v169
	v_add_f32_e32 v170, v170, v171
	v_add_f32_e32 v184, v184, v185
	v_add_f32_e32 v186, v186, v187
	v_add_f32_e32 v188, v188, v189
	v_add_f32_e32 v190, v190, v191
	v_add_f32_e32 v192, v192, v193
	v_add_f32_e32 v194, v194, v195
	v_add_f32_e32 v128, v128, v130
	v_add_f32_e32 v156, v156, v158
	v_add_f32_e32 v160, v160, v162
	v_add_f32_e32 v164, v164, v166
	v_add_f32_e32 v168, v168, v170
	v_add_f32_e32 v184, v184, v186
	v_add_f32_e32 v188, v188, v190
	v_add_f32_e32 v192, v192, v194
	ds_bpermute_b32 v129, v197, v128
	ds_bpermute_b32 v157, v197, v156
	ds_bpermute_b32 v161, v197, v160
	ds_bpermute_b32 v165, v197, v164
	ds_bpermute_b32 v169, v197, v168
	ds_bpermute_b32 v185, v197, v184
	ds_bpermute_b32 v189, v197, v188
	ds_bpermute_b32 v193, v197, v192
	s_waitcnt lgkmcnt(0)
	v_add_f32_e32 v128, v128, v129
	v_add_f32_e32 v156, v156, v157
	v_add_f32_e32 v160, v160, v161
	v_add_f32_e32 v164, v164, v165
	v_add_f32_e32 v168, v168, v169
	v_add_f32_e32 v184, v184, v185
	v_add_f32_e32 v188, v188, v189
	v_add_f32_e32 v192, v192, v193
	ds_bpermute_b32 v129, v198, v128
	ds_bpermute_b32 v157, v198, v156
	ds_bpermute_b32 v161, v198, v160
	ds_bpermute_b32 v165, v198, v164
	ds_bpermute_b32 v169, v198, v168
	ds_bpermute_b32 v185, v198, v184
	ds_bpermute_b32 v189, v198, v188
	ds_bpermute_b32 v193, v198, v192
	s_waitcnt lgkmcnt(0)
	v_add_f32_e32 v128, v128, v129
	v_add_f32_e32 v156, v156, v157
	v_add_f32_e32 v160, v160, v161
	v_add_f32_e32 v164, v164, v165
	v_add_f32_e32 v168, v168, v169
	v_add_f32_e32 v184, v184, v185
	v_add_f32_e32 v188, v188, v189
	v_add_f32_e32 v192, v192, v193
	v_fmamk_f32 v128, v128, 0x3a800000, v181
	v_fmamk_f32 v156, v156, 0x3a800000, v181
	v_fmamk_f32 v160, v160, 0x3a800000, v181
	v_fmamk_f32 v164, v164, 0x3a800000, v181
	v_fmamk_f32 v168, v168, 0x3a800000, v181
	v_fmamk_f32 v184, v184, 0x3a800000, v181
	v_fmamk_f32 v188, v188, 0x3a800000, v181
	v_fmamk_f32 v192, v192, 0x3a800000, v181
	v_rsq_f32_e32 v128, v128
	v_rsq_f32_e32 v156, v156
	v_rsq_f32_e32 v160, v160
	v_rsq_f32_e32 v164, v164
	v_rsq_f32_e32 v168, v168
	v_rsq_f32_e32 v184, v184
	v_rsq_f32_e32 v188, v188
	v_rsq_f32_e32 v192, v192
	s_nop 0
	v_mul_f32_e32 v128, v128, v199
	v_mul_f32_e32 v156, v156, v199
	v_mul_f32_e32 v160, v160, v199
	v_mul_f32_e32 v164, v164, v199
	v_mul_f32_e32 v168, v168, v199
	v_mul_f32_e32 v184, v184, v199
	v_mul_f32_e32 v188, v188, v199
	v_mul_f32_e32 v192, v192, v199
	v_mov_b32_e32 v252, v250
	v_mov_b32_e32 v253, v251
	v_pk_mul_f32 v[120:121], v[120:121], v[128:129] op_sel_hi:[1,0]
	v_pk_mul_f32 v[122:123], v[122:123], v[128:129] op_sel_hi:[1,0]
	v_pk_mul_f32 v[124:125], v[124:125], v[128:129] op_sel_hi:[1,0]
	v_pk_mul_f32 v[126:127], v[126:127], v[128:129] op_sel_hi:[1,0]
	v_cvt_pk_bf16_f32 v200, v120, v121
	v_cvt_pk_bf16_f32 v201, v122, v123
	v_cvt_pk_bf16_f32 v202, v124, v125
	v_cvt_pk_bf16_f32 v203, v126, v127
	global_store_dwordx4 v252, v[200:203], s[50:51]
	v_pk_mul_f32 v[116:117], v[116:117], v[128:129] op_sel_hi:[1,0]
	v_pk_mul_f32 v[118:119], v[118:119], v[128:129] op_sel_hi:[1,0]
	v_pk_mul_f32 v[112:113], v[112:113], v[128:129] op_sel_hi:[1,0]
	v_pk_mul_f32 v[114:115], v[114:115], v[128:129] op_sel_hi:[1,0]
	v_cvt_pk_bf16_f32 v208, v116, v117
	v_cvt_pk_bf16_f32 v209, v118, v119
	v_cvt_pk_bf16_f32 v210, v112, v113
	v_cvt_pk_bf16_f32 v211, v114, v115
	global_store_dwordx4 v252, v[208:211], s[50:51] offset:256
	s_cmp_eq_u32 s38, 0
	s_cbranch_scc1 .Lin0_s0
	global_store_dwordx4 v253, v[120:123], s[58:59] nt
	global_store_dwordx4 v253, v[124:127], s[58:59] offset:16 nt
	global_store_dwordx4 v253, v[116:119], s[58:59] offset:512 nt
	global_store_dwordx4 v253, v[112:115], s[58:59] offset:528 nt
; __device__ __forceinline__ void st_nt(float* p, const f32x4 v) { __builtin_nontemporal_store(v, (f32x4*)p); }
;     __device__ __forceinline__ void operator()(AccRef acc, const pg8::Unit& u, int wr, int wc, int fr, int fq) const {
;     ...
;         for (int ai = 0; ai < 2; ++ai)
; #pragma unroll
;             for (int m = 0; m < 4; ++m) {
;                 const int row = row0 + ai * 128 + m * 16;
;                 const float rs = rs_from(ssp + (size_t)row * 16, 4, 1.0f / 1024.0f);
;                 const float sc = rs * qs;
; #pragma unroll
;                 for (int bj = 0; bj < 2; ++bj) {
;                     const int cs = cs0 + bj * 128;
;                     const f32x4 a = acc[ai][bj][m][0] * sc, b = acc[ai][bj][m][1] * sc;
;                     const u32x4 w = pack8(a, b);
;                     *(u32x4*)(tok + (size_t)row * 512 + cs) = w;
;                     if (sec == 0 || sec == 3) continue;
;                     float* fo = nullptr;
;                     if (!sample) {
;                         const int b_ = row >> 11, t = row & 2047;
;                         if (sec == 1 || sec == 2) { if ((u.pm & 7) >= 6) fo = out + (sec == 1 ? O_PAK : O_PAV) + ((size_t)b_ * 512 + (t - 1536)) * 512 + cs; }
;                         else fo = out + (sec == 4 ? O_PBK : O_PBV) + (size_t)row * 512 + cs;
;                     } else {
;                         const int sr = row - TP, b_ = sr >> 4, t = sr & 15;
;                         const size_t so = (sec == 1) ? O_SAK : (sec == 2) ? O_SAV : (sec == 4) ? O_SBK : O_SBV;
;                         fo = out + so + (size_t)sr * 512 + cs;
;                         bf16_t* cat = (sec == 1) ? (bf16_t*)(ws + WS_KAS) + ((size_t)b_ * KA_ROWS + 512 + t) * 512
;                                     : (sec == 2) ? (bf16_t*)(ws + WS_VAS) + ((size_t)b_ * KA_ROWS + 512 + t) * 512
;                                     : (sec == 4) ? (bf16_t*)(ws + WS_KBS) + ((size_t)b_ * KB_ROWS + 1024 + t) * 512
;                                                  : (bf16_t*)(ws + WS_VBS) + ((size_t)b_ * KB_ROWS + 1024 + t) * 512;
;                         *(u32x4*)(cat + cs) = w;
;                     }
;                     if (fo) { st_nt(fo, a); st_nt(fo + 4, b); }
;                 }
.Lin0_s0:
	v_add_u32_e32 v252, 0x4000, v250
	v_add_u32_e32 v253, 0x8000, v251
	v_pk_mul_f32 v[108:109], v[108:109], v[156:157] op_sel_hi:[1,0]
	v_pk_mul_f32 v[110:111], v[110:111], v[156:157] op_sel_hi:[1,0]
	v_pk_mul_f32 v[104:105], v[104:105], v[156:157] op_sel_hi:[1,0]
	v_pk_mul_f32 v[106:107], v[106:107], v[156:157] op_sel_hi:[1,0]
	v_cvt_pk_bf16_f32 v204, v108, v109
	v_cvt_pk_bf16_f32 v205, v110, v111
	v_cvt_pk_bf16_f32 v206, v104, v105
	v_cvt_pk_bf16_f32 v207, v106, v107
	global_store_dwordx4 v252, v[204:207], s[50:51]
	v_pk_mul_f32 v[100:101], v[100:101], v[156:157] op_sel_hi:[1,0]
	v_pk_mul_f32 v[102:103], v[102:103], v[156:157] op_sel_hi:[1,0]
	v_pk_mul_f32 v[96:97], v[96:97], v[156:157] op_sel_hi:[1,0]
	v_pk_mul_f32 v[98:99], v[98:99], v[156:157] op_sel_hi:[1,0]
	v_cvt_pk_bf16_f32 v208, v100, v101
	v_cvt_pk_bf16_f32 v209, v102, v103
	v_cvt_pk_bf16_f32 v210, v96, v97
	v_cvt_pk_bf16_f32 v211, v98, v99
	global_store_dwordx4 v252, v[208:211], s[50:51] offset:256
	s_cmp_eq_u32 s38, 0
	s_cbranch_scc1 .Lin0_s1
	global_store_dwordx4 v253, v[108:111], s[58:59] nt
	global_store_dwordx4 v253, v[104:107], s[58:59] offset:16 nt
	global_store_dwordx4 v253, v[100:103], s[58:59] offset:512 nt
	global_store_dwordx4 v253, v[96:99], s[58:59] offset:528 nt
.Lin0_s1:
	v_add_u32_e32 v252, 0x8000, v250
	v_add_u32_e32 v253, 0x10000, v251
	v_pk_mul_f32 v[92:93], v[92:93], v[160:161] op_sel_hi:[1,0]
	v_pk_mul_f32 v[94:95], v[94:95], v[160:161] op_sel_hi:[1,0]
	v_pk_mul_f32 v[88:89], v[88:89], v[160:161] op_sel_hi:[1,0]
	v_pk_mul_f32 v[90:91], v[90:91], v[160:161] op_sel_hi:[1,0]
	v_cvt_pk_bf16_f32 v200, v92, v93
	v_cvt_pk_bf16_f32 v201, v94, v95
	v_cvt_pk_bf16_f32 v202, v88, v89
	v_cvt_pk_bf16_f32 v203, v90, v91
	global_store_dwordx4 v252, v[200:203], s[50:51]
	v_pk_mul_f32 v[84:85], v[84:85], v[160:161] op_sel_hi:[1,0]
	v_pk_mul_f32 v[86:87], v[86:87], v[160:161] op_sel_hi:[1,0]
	v_pk_mul_f32 v[80:81], v[80:81], v[160:161] op_sel_hi:[1,0]
	v_pk_mul_f32 v[82:83], v[82:83], v[160:161] op_sel_hi:[1,0]
	v_cvt_pk_bf16_f32 v208, v84, v85
	v_cvt_pk_bf16_f32 v209, v86, v87
	v_cvt_pk_bf16_f32 v210, v80, v81
	v_cvt_pk_bf16_f32 v211, v82, v83
	global_store_dwordx4 v252, v[208:211], s[50:51] offset:256
	s_cmp_eq_u32 s38, 0
	s_cbranch_scc1 .Lin0_s2
	global_store_dwordx4 v253, v[92:95], s[58:59] nt
	global_store_dwordx4 v253, v[88:91], s[58:59] offset:16 nt
	global_store_dwordx4 v253, v[84:87], s[58:59] offset:512 nt
	global_store_dwordx4 v253, v[80:83], s[58:59] offset:528 nt
.Lin0_s2:
	v_add_u32_e32 v252, 0xc000, v250
	v_add_u32_e32 v253, 0x18000, v251
	v_pk_mul_f32 v[76:77], v[76:77], v[164:165] op_sel_hi:[1,0]
	v_pk_mul_f32 v[78:79], v[78:79], v[164:165] op_sel_hi:[1,0]
	v_pk_mul_f32 v[72:73], v[72:73], v[164:165] op_sel_hi:[1,0]
	v_pk_mul_f32 v[74:75], v[74:75], v[164:165] op_sel_hi:[1,0]
	v_cvt_pk_bf16_f32 v204, v76, v77
	v_cvt_pk_bf16_f32 v205, v78, v79
	v_cvt_pk_bf16_f32 v206, v72, v73
	v_cvt_pk_bf16_f32 v207, v74, v75
	global_store_dwordx4 v252, v[204:207], s[50:51]
	v_pk_mul_f32 v[68:69], v[68:69], v[164:165] op_sel_hi:[1,0]
	v_pk_mul_f32 v[70:71], v[70:71], v[164:165] op_sel_hi:[1,0]
	v_pk_mul_f32 v[64:65], v[64:65], v[164:165] op_sel_hi:[1,0]
	v_pk_mul_f32 v[66:67], v[66:67], v[164:165] op_sel_hi:[1,0]
	v_cvt_pk_bf16_f32 v208, v68, v69
	v_cvt_pk_bf16_f32 v209, v70, v71
	v_cvt_pk_bf16_f32 v210, v64, v65
	v_cvt_pk_bf16_f32 v211, v66, v67
	global_store_dwordx4 v252, v[208:211], s[50:51] offset:256
	s_cmp_eq_u32 s38, 0
	s_cbranch_scc1 .Lin0_s3
	global_store_dwordx4 v253, v[76:79], s[58:59] nt
	global_store_dwordx4 v253, v[72:75], s[58:59] offset:16 nt
	global_store_dwordx4 v253, v[68:71], s[58:59] offset:512 nt
	global_store_dwordx4 v253, v[64:67], s[58:59] offset:528 nt
.Lin0_s3:
	v_add_u32_e32 v252, 0x20000, v250
	v_add_u32_e32 v253, 0x40000, v251
	v_pk_mul_f32 v[60:61], v[60:61], v[168:169] op_sel_hi:[1,0]
	v_pk_mul_f32 v[62:63], v[62:63], v[168:169] op_sel_hi:[1,0]
	v_pk_mul_f32 v[56:57], v[56:57], v[168:169] op_sel_hi:[1,0]
	v_pk_mul_f32 v[58:59], v[58:59], v[168:169] op_sel_hi:[1,0]
	v_cvt_pk_bf16_f32 v200, v60, v61
	v_cvt_pk_bf16_f32 v201, v62, v63
	v_cvt_pk_bf16_f32 v202, v56, v57
	v_cvt_pk_bf16_f32 v203, v58, v59
	global_store_dwordx4 v252, v[200:203], s[50:51]
	v_pk_mul_f32 v[52:53], v[52:53], v[168:169] op_sel_hi:[1,0]
	v_pk_mul_f32 v[54:55], v[54:55], v[168:169] op_sel_hi:[1,0]
	v_pk_mul_f32 v[48:49], v[48:49], v[168:169] op_sel_hi:[1,0]
	v_pk_mul_f32 v[50:51], v[50:51], v[168:169] op_sel_hi:[1,0]
	v_cvt_pk_bf16_f32 v208, v52, v53
	v_cvt_pk_bf16_f32 v209, v54, v55
	v_cvt_pk_bf16_f32 v210, v48, v49
	v_cvt_pk_bf16_f32 v211, v50, v51
	global_store_dwordx4 v252, v[208:211], s[50:51] offset:256
	s_cmp_eq_u32 s38, 0
	s_cbranch_scc1 .Lin0_s4
	global_store_dwordx4 v253, v[60:63], s[58:59] nt
	global_store_dwordx4 v253, v[56:59], s[58:59] offset:16 nt
	global_store_dwordx4 v253, v[52:55], s[58:59] offset:512 nt
	global_store_dwordx4 v253, v[48:51], s[58:59] offset:528 nt
; __device__ __forceinline__ void st_nt(float* p, const f32x4 v) { __builtin_nontemporal_store(v, (f32x4*)p); }
;     __device__ __forceinline__ void operator()(AccRef acc, const pg8::Unit& u, int wr, int wc, int fr, int fq) const {
;     ...
;         for (int ai = 0; ai < 2; ++ai)
; #pragma unroll
;             for (int m = 0; m < 4; ++m) {
;                 const int row = row0 + ai * 128 + m * 16;
;                 const float rs = rs_from(ssp + (size_t)row * 16, 4, 1.0f / 1024.0f);
;                 const float sc = rs * qs;
; #pragma unroll
;                 for (int bj = 0; bj < 2; ++bj) {
;                     const int cs = cs0 + bj * 128;
;                     const f32x4 a = acc[ai][bj][m][0] * sc, b = acc[ai][bj][m][1] * sc;
;                     const u32x4 w = pack8(a, b);
;                     *(u32x4*)(tok + (size_t)row * 512 + cs) = w;
;                     if (sec == 0 || sec == 3) continue;
;                     float* fo = nullptr;
;                     if (!sample) {
;                         const int b_ = row >> 11, t = row & 2047;
;                         if (sec == 1 || sec == 2) { if ((u.pm & 7) >= 6) fo = out + (sec == 1 ? O_PAK : O_PAV) + ((size_t)b_ * 512 + (t - 1536)) * 512 + cs; }
;                         else fo = out + (sec == 4 ? O_PBK : O_PBV) + (size_t)row * 512 + cs;
;                     } else {
;                         const int sr = row - TP, b_ = sr >> 4, t = sr & 15;
;                         const size_t so = (sec == 1) ? O_SAK : (sec == 2) ? O_SAV : (sec == 4) ? O_SBK : O_SBV;
;                         fo = out + so + (size_t)sr * 512 + cs;
;                         bf16_t* cat = (sec == 1) ? (bf16_t*)(ws + WS_KAS) + ((size_t)b_ * KA_ROWS + 512 + t) * 512
;                                     : (sec == 2) ? (bf16_t*)(ws + WS_VAS) + ((size_t)b_ * KA_ROWS + 512 + t) * 512
;                                     : (sec == 4) ? (bf16_t*)(ws + WS_KBS) + ((size_t)b_ * KB_ROWS + 1024 + t) * 512
;                                                  : (bf16_t*)(ws + WS_VBS) + ((size_t)b_ * KB_ROWS + 1024 + t) * 512;
;                         *(u32x4*)(cat + cs) = w;
;                     }
;                     if (fo) { st_nt(fo, a); st_nt(fo + 4, b); }
.Lin0_s4:
	v_add_u32_e32 v252, 0x24000, v250
	v_add_u32_e32 v253, 0x48000, v251
	v_pk_mul_f32 v[44:45], v[44:45], v[184:185] op_sel_hi:[1,0]
	v_pk_mul_f32 v[46:47], v[46:47], v[184:185] op_sel_hi:[1,0]
	v_pk_mul_f32 v[40:41], v[40:41], v[184:185] op_sel_hi:[1,0]
	v_pk_mul_f32 v[42:43], v[42:43], v[184:185] op_sel_hi:[1,0]
	v_cvt_pk_bf16_f32 v204, v44, v45
	v_cvt_pk_bf16_f32 v205, v46, v47
	v_cvt_pk_bf16_f32 v206, v40, v41
	v_cvt_pk_bf16_f32 v207, v42, v43
	global_store_dwordx4 v252, v[204:207], s[50:51]
	v_pk_mul_f32 v[36:37], v[36:37], v[184:185] op_sel_hi:[1,0]
	v_pk_mul_f32 v[38:39], v[38:39], v[184:185] op_sel_hi:[1,0]
	v_pk_mul_f32 v[32:33], v[32:33], v[184:185] op_sel_hi:[1,0]
	v_pk_mul_f32 v[34:35], v[34:35], v[184:185] op_sel_hi:[1,0]
	v_cvt_pk_bf16_f32 v208, v36, v37
	v_cvt_pk_bf16_f32 v209, v38, v39
	v_cvt_pk_bf16_f32 v210, v32, v33
	v_cvt_pk_bf16_f32 v211, v34, v35
	global_store_dwordx4 v252, v[208:211], s[50:51] offset:256
	s_cmp_eq_u32 s38, 0
	s_cbranch_scc1 .Lin0_s5
	global_store_dwordx4 v253, v[44:47], s[58:59] nt
	global_store_dwordx4 v253, v[40:43], s[58:59] offset:16 nt
	global_store_dwordx4 v253, v[36:39], s[58:59] offset:512 nt
	global_store_dwordx4 v253, v[32:35], s[58:59] offset:528 nt
.Lin0_s5:
	v_add_u32_e32 v252, 0x28000, v250
	v_add_u32_e32 v253, 0x50000, v251
	v_pk_mul_f32 v[28:29], v[28:29], v[188:189] op_sel_hi:[1,0]
	v_pk_mul_f32 v[30:31], v[30:31], v[188:189] op_sel_hi:[1,0]
	v_pk_mul_f32 v[24:25], v[24:25], v[188:189] op_sel_hi:[1,0]
	v_pk_mul_f32 v[26:27], v[26:27], v[188:189] op_sel_hi:[1,0]
	v_cvt_pk_bf16_f32 v200, v28, v29
	v_cvt_pk_bf16_f32 v201, v30, v31
	v_cvt_pk_bf16_f32 v202, v24, v25
	v_cvt_pk_bf16_f32 v203, v26, v27
	global_store_dwordx4 v252, v[200:203], s[50:51]
	v_pk_mul_f32 v[20:21], v[20:21], v[188:189] op_sel_hi:[1,0]
	v_pk_mul_f32 v[22:23], v[22:23], v[188:189] op_sel_hi:[1,0]
	v_pk_mul_f32 v[16:17], v[16:17], v[188:189] op_sel_hi:[1,0]
	v_pk_mul_f32 v[18:19], v[18:19], v[188:189] op_sel_hi:[1,0]
	v_cvt_pk_bf16_f32 v208, v20, v21
	v_cvt_pk_bf16_f32 v209, v22, v23
	v_cvt_pk_bf16_f32 v210, v16, v17
	v_cvt_pk_bf16_f32 v211, v18, v19
	global_store_dwordx4 v252, v[208:211], s[50:51] offset:256
	s_cmp_eq_u32 s38, 0
	s_cbranch_scc1 .Lin0_s6
	global_store_dwordx4 v253, v[28:31], s[58:59] nt
	global_store_dwordx4 v253, v[24:27], s[58:59] offset:16 nt
	global_store_dwordx4 v253, v[20:23], s[58:59] offset:512 nt
	global_store_dwordx4 v253, v[16:19], s[58:59] offset:528 nt
.Lin0_s6:
	v_add_u32_e32 v252, 0x2c000, v250
	v_add_u32_e32 v253, 0x58000, v251
	v_pk_mul_f32 v[12:13], v[12:13], v[192:193] op_sel_hi:[1,0]
	v_pk_mul_f32 v[14:15], v[14:15], v[192:193] op_sel_hi:[1,0]
	v_pk_mul_f32 v[8:9], v[8:9], v[192:193] op_sel_hi:[1,0]
	v_pk_mul_f32 v[10:11], v[10:11], v[192:193] op_sel_hi:[1,0]
	v_cvt_pk_bf16_f32 v204, v12, v13
	v_cvt_pk_bf16_f32 v205, v14, v15
	v_cvt_pk_bf16_f32 v206, v8, v9
	v_cvt_pk_bf16_f32 v207, v10, v11
	global_store_dwordx4 v252, v[204:207], s[50:51]
	v_pk_mul_f32 v[4:5], v[4:5], v[192:193] op_sel_hi:[1,0]
	v_pk_mul_f32 v[6:7], v[6:7], v[192:193] op_sel_hi:[1,0]
	v_pk_mul_f32 v[0:1], v[0:1], v[192:193] op_sel_hi:[1,0]
	v_pk_mul_f32 v[2:3], v[2:3], v[192:193] op_sel_hi:[1,0]
	v_cvt_pk_bf16_f32 v208, v4, v5
	v_cvt_pk_bf16_f32 v209, v6, v7
	v_cvt_pk_bf16_f32 v210, v0, v1
	v_cvt_pk_bf16_f32 v211, v2, v3
	global_store_dwordx4 v252, v[208:211], s[50:51] offset:256
	s_cmp_eq_u32 s38, 0
	s_cbranch_scc1 .Lin0_s7
	global_store_dwordx4 v253, v[12:15], s[58:59] nt
	global_store_dwordx4 v253, v[8:11], s[58:59] offset:16 nt
	global_store_dwordx4 v253, v[4:7], s[58:59] offset:512 nt
	global_store_dwordx4 v253, v[0:3], s[58:59] offset:528 nt
.Lin0_s7:
.Lin0_end:
.LBB0_760:
	s_and_b64 vcc, exec, s[2:3]
	s_mov_b64 s[2:3], -1
	s_cbranch_vccnz .LBB0_588
	s_andn2_b64 vcc, exec, s[74:75]
	s_cbranch_vccnz .LBB0_587
	s_barrier
	s_branch .LBB0_587
